# attention first half: the second-16-score scaling ops issued in the last P.V gaps right after the last MFMA that reads each destination register
# baseline (speedup 1.0000x reference)
; __device__ __forceinline__ void finishSM(f32x16& p0, f32x16& p1, float alpha, float& l_reg, bf16x8& pa0, bf16x8& pa1, bf16x8& pa2, bf16x8& pa3) {
; #pragma unroll
;     for (int r = 0; r < 16; ++r) p1[r] = __builtin_amdgcn_exp2f(p1[r]);
;     float ps = 0;
; #pragma unroll
;     for (int r = 0; r < 16; ++r) ps += p0[r];
; #pragma unroll
;     for (int r = 0; r < 16; ++r) ps += p1[r];
;     { auto rr = __builtin_amdgcn_permlane32_swap(__float_as_uint(ps), __float_as_uint(ps), false, false);
;       ps = __uint_as_float(rr[0]) + __uint_as_float(rr[1]); }
;     l_reg = l_reg * alpha + ps;
;     ...
;     PK4(p0, 0, pa0); PK4(p0, 8, pa1); PK4(p1, 0, pa2); PK4(p1, 8, pa3);
;     ...
; }
; __device__ __forceinline__ void qkt(f32x16& p0, f32x16& p1, const char* Ks, const bf16x8* qr, int r32, int hi, int comp) {
;     p0 = f32x16{}; p1 = f32x16{};
; #pragma unroll
;     for (int d0 = 0; d0 < 4; ++d0) { const int cb = (comp * 64 + d0 * 16 + hi * 8) * 2;
;         const bf16x8 b0 = *reinterpret_cast<const bf16x8*>(Ks + KSWZ(r32, cb));
;         const bf16x8 b1 = *reinterpret_cast<const bf16x8*>(Ks + KSWZ(32 + r32, cb));
;         p0 = __builtin_amdgcn_mfma_f32_32x32x16_bf16(b0, qr[d0], p0, 0, 0, 0);
;         p1 = __builtin_amdgcn_mfma_f32_32x32x16_bf16(b1, qr[d0], p1, 0, 0, 0); }
; }
; __device__ __forceinline__ int v_st(int k, int c) { const int kk = (k & ~0xC) | ((k & 4) << 1) | ((k & 8) >> 1); return ((kk >> 3) * 4 + (c >> 5)) * 512 + ((kk & 7) * 32 + (c & 31)) * 2; }
; __device__ __forceinline__ int v_rd_base(int lane) { return ((lane & 3) << 3) | (((lane >> 2) & 3) << 6) | (((lane >> 4) & 1) << 5) | (((lane >> 5) & 1) << 8); }
; template <int OFF> __device__ __forceinline__ s16x4 tr_read(int vb) {
;     s16x4 r; asm volatile("ds_read_b64_tr_b16 %0, %1 offset:%2" : "=&v"(r) : "v"(vb), "i"(OFF) : "memory"); return r;
; }
; template <int D0> __device__ __forceinline__ void pv_one(f32x16& od, int vb, bf16x8 pa0, bf16x8 pa1, bf16x8 pa2, bf16x8 pa3) {
;     const s16x4 l0 = tr_read<v_rd_off(D0, 0, 0)>(vb), h0 = tr_read<v_rd_off(D0, 0, 1)>(vb), l1 = tr_read<v_rd_off(D0, 1, 0)>(vb), h1 = tr_read<v_rd_off(D0, 1, 1)>(vb);
;     const s16x4 l2 = tr_read<v_rd_off(D0, 2, 0)>(vb), h2 = tr_read<v_rd_off(D0, 2, 1)>(vb), l3 = tr_read<v_rd_off(D0, 3, 0)>(vb), h3 = tr_read<v_rd_off(D0, 3, 1)>(vb);
;     asm volatile("s_waitcnt lgkmcnt(0)" ::: "memory"); SBAR();
.LBB0_262:
	ds_read_b128 v[64:67], v170 offset:49152
	ds_read_b128 v[68:71], v170 offset:57344
	v_add_f32_e32 v177, 0, v240
	v_add_f32_e32 v177, v241, v177
	v_add_f32_e32 v177, v242, v177
	s_waitcnt lgkmcnt(1)
	v_mfma_f32_32x32x16_bf16 v[80:95], v[64:67], v[110:113], 0
	v_add_f32_e32 v177, v243, v177
	v_add_f32_e32 v177, v244, v177
	ds_read_b128 v[178:181], v171 offset:49152
	ds_read_b128 v[220:223], v171 offset:57344
	v_add_f32_e32 v177, v245, v177
	v_add_f32_e32 v177, v246, v177
	v_add_f32_e32 v177, v247, v177
	v_add_f32_e32 v177, v248, v177
	s_waitcnt lgkmcnt(2)
	v_mfma_f32_32x32x16_bf16 v[64:79], v[68:71], v[110:113], 0
	v_add_f32_e32 v177, v249, v177
	v_add_f32_e32 v177, v250, v177
	v_add_f32_e32 v177, v251, v177
	v_exp_f32_e32 v128, v128
	v_add_f32_e32 v177, v206, v177
	v_exp_f32_e32 v129, v129
	v_add_f32_e32 v177, v207, v177
	s_waitcnt lgkmcnt(1)
	v_mfma_f32_32x32x16_bf16 v[80:95], v[178:181], v[106:109], v[80:95]
	v_exp_f32_e32 v126, v126
	v_add_f32_e32 v177, v208, v177
	v_exp_f32_e32 v127, v127
	v_add_f32_e32 v177, v209, v177
	v_exp_f32_e32 v122, v122
	v_add_f32_e32 v177, v128, v177
	v_exp_f32_e32 v123, v123
	s_waitcnt lgkmcnt(0)
	v_mfma_f32_32x32x16_bf16 v[64:79], v[220:223], v[106:109], v[64:79]
	ds_read_b128 v[178:181], v173 offset:49152
	ds_read_b128 v[220:223], v173 offset:57344
	v_add_f32_e32 v177, v129, v177
	v_exp_f32_e32 v118, v118
	v_add_f32_e32 v177, v126, v177
	v_exp_f32_e32 v119, v119
	v_add_f32_e32 v177, v127, v177
	v_exp_f32_e32 v116, v116
	s_waitcnt lgkmcnt(1)
	v_mfma_f32_32x32x16_bf16 v[80:95], v[178:181], v[102:105], v[80:95]
	v_add_f32_e32 v177, v122, v177
	v_exp_f32_e32 v117, v117
	v_add_f32_e32 v177, v123, v177
	v_exp_f32_e32 v124, v124
	v_add_f32_e32 v177, v118, v177
	v_exp_f32_e32 v125, v125
	v_add_f32_e32 v177, v119, v177
	s_waitcnt lgkmcnt(0)
	v_mfma_f32_32x32x16_bf16 v[64:79], v[220:223], v[102:105], v[64:79]
	ds_read_b128 v[178:181], v172 offset:49152
	ds_read_b128 v[220:223], v172 offset:57344
	v_exp_f32_e32 v120, v120
	v_add_f32_e32 v177, v116, v177
	v_exp_f32_e32 v121, v121
	v_add_f32_e32 v177, v117, v177
	v_exp_f32_e32 v114, v114
	v_add_f32_e32 v177, v124, v177
	s_waitcnt lgkmcnt(1)
	v_mfma_f32_32x32x16_bf16 v[80:95], v[178:181], v[98:101], v[80:95]
	v_exp_f32_e32 v115, v115
	v_add_f32_e32 v177, v125, v177
	v_add_f32_e32 v177, v120, v177
	v_add_f32_e32 v177, v121, v177
	v_add_f32_e32 v177, v114, v177
	v_add_f32_e32 v177, v115, v177
	v_mov_b32_e32 v178, v177
	s_waitcnt lgkmcnt(0)
	v_mfma_f32_32x32x16_bf16 v[64:79], v[220:223], v[98:101], v[64:79]
	v_cvt_pk_bf16_f32 v212, v240, v241
	v_cvt_pk_bf16_f32 v213, v242, v243
	v_cvt_pk_bf16_f32 v214, v244, v245
	v_cvt_pk_bf16_f32 v215, v246, v247
	v_cvt_pk_bf16_f32 v180, v248, v249
	v_cvt_pk_bf16_f32 v181, v250, v251
	v_cvt_pk_bf16_f32 v182, v206, v207
	v_permlane32_swap_b32_e32 v177, v178
	v_cvt_pk_bf16_f32 v183, v208, v209
	v_permlane32_swap_b32_e32 v180, v182
	v_cvt_pk_bf16_f32 v184, v128, v129
	v_cvt_pk_bf16_f32 v185, v126, v127
	v_cvt_pk_bf16_f32 v186, v122, v123
	v_cvt_pk_bf16_f32 v187, v118, v119
	v_cvt_pk_bf16_f32 v216, v116, v117
	v_cvt_pk_bf16_f32 v217, v124, v125
	v_cvt_pk_bf16_f32 v218, v120, v121
	v_cvt_pk_bf16_f32 v219, v114, v115
	v_permlane32_swap_b32_e32 v212, v214
	v_permlane32_swap_b32_e32 v213, v215
	v_permlane32_swap_b32_e32 v181, v183
	v_permlane32_swap_b32_e32 v184, v186
	v_permlane32_swap_b32_e32 v185, v187
	v_permlane32_swap_b32_e32 v216, v218
	v_permlane32_swap_b32_e32 v217, v219
	v_add_u32_e32 v122, 0x10000, v176
	global_load_dwordx4 v[240:243], v176, s[58:59]
	global_load_dwordx4 v[244:247], v176, s[28:29]
	global_load_dwordx4 v[206:209], v122, s[58:59]
	s_nop 0
	global_load_dwordx4 v[248:251], v122, s[28:29]
	ds_read_b64_tr_b16 v[220:221], v160 offset:0
	ds_read_b64_tr_b16 v[222:223], v160 offset:0x800
	ds_read_b64_tr_b16 v[224:225], v160 offset:0x1000
	ds_read_b64_tr_b16 v[226:227], v160 offset:0x1800
	ds_read_b64_tr_b16 v[228:229], v160 offset:0x2000
	ds_read_b64_tr_b16 v[230:231], v160 offset:0x2800
	ds_read_b64_tr_b16 v[232:233], v160 offset:0x3000
	ds_read_b64_tr_b16 v[234:235], v160 offset:0x3800
	s_waitcnt lgkmcnt(0)
	v_mfma_f32_32x32x16_bf16 v[48:63], v[212:215], v[220:223], v[48:63]
	ds_read_b64_tr_b16 v[220:221], v160 offset:0x200
	ds_read_b64_tr_b16 v[222:223], v160 offset:0xa00
	v_max_f32_e32 v179, v81, v81
	v_max_f32_e32 v255, v80, v80
	v_max_f32_e32 v179, v255, v179
	v_max3_f32 v179, v179, v82, v83
	v_max3_f32 v179, v179, v84, v85
	v_mfma_f32_32x32x16_bf16 v[48:63], v[180:183], v[224:227], v[48:63]
	ds_read_b64_tr_b16 v[224:225], v160 offset:0x1200
	ds_read_b64_tr_b16 v[226:227], v160 offset:0x1a00
	v_max3_f32 v179, v179, v86, v87
	v_max3_f32 v179, v179, v88, v89
	v_max3_f32 v179, v179, v90, v91
	v_max3_f32 v179, v179, v92, v93
	v_max3_f32 v179, v179, v94, v95
	v_mfma_f32_32x32x16_bf16 v[48:63], v[184:187], v[228:231], v[48:63]
	ds_read_b64_tr_b16 v[228:229], v160 offset:0x2200
	ds_read_b64_tr_b16 v[230:231], v160 offset:0x2a00
	v_max3_f32 v179, v179, v64, v65
	v_max3_f32 v179, v179, v66, v67
	v_max3_f32 v179, v179, v68, v69
	v_max3_f32 v179, v179, v70, v71
	v_max3_f32 v179, v179, v72, v73
	v_mfma_f32_32x32x16_bf16 v[48:63], v[216:219], v[232:235], v[48:63]
	ds_read_b64_tr_b16 v[232:233], v160 offset:0x3200
	ds_read_b64_tr_b16 v[234:235], v160 offset:0x3a00
	v_max3_f32 v179, v179, v74, v75
	v_max3_f32 v179, v179, v76, v77
	v_max3_f32 v179, v179, v78, v79
	v_mov_b32_e32 v255, v179
	s_nop 1
	v_permlane32_swap_b32_e32 v179, v255
	s_waitcnt lgkmcnt(0)
; __device__ __forceinline__ void partialSM(f32x16& p0, f32x16& p1, float& m_reg, float& mn, float& alpha) {
;     constexpr float C = SCALE * 1.4426950408889634f;
;     float pmax = p0[0];
; #pragma unroll
;     for (int r = 1; r < 16; ++r) pmax = fmaxf(pmax, p0[r]);
; #pragma unroll
;     for (int r = 0; r < 16; ++r) pmax = fmaxf(pmax, p1[r]);
;     { auto rr = __builtin_amdgcn_permlane32_swap(__float_as_uint(pmax), __float_as_uint(pmax), false, false);
;       pmax = fmaxf(__uint_as_float(rr[0]), __uint_as_float(rr[1])); }
;     if (__builtin_expect(__all(pmax - m_reg <= THR / SCALE), 1)) { mn = m_reg; alpha = 1.f; }
;     else { mn = fmaxf(m_reg, pmax); alpha = __builtin_amdgcn_exp2f((m_reg - mn) * C); m_reg = mn; }
;     const float mnC = -mn * C;
; #pragma unroll
;     for (int r = 0; r < 16; ++r) p0[r] = fmaf(p0[r], C, mnC);
; #pragma unroll
;     for (int r = 0; r < 16; ++r) p1[r] = fmaf(p1[r], C, mnC);
; #pragma unroll
;     for (int r = 0; r < 16; ++r) p0[r] = __builtin_amdgcn_exp2f(p0[r]);
; }
	v_mfma_f32_32x32x16_bf16 v[32:47], v[212:215], v[220:223], v[32:47]
	ds_read_b64_tr_b16 v[220:221], v160 offset:0x400
	ds_read_b64_tr_b16 v[222:223], v160 offset:0xc00
	v_max_f32_e32 v255, v255, v255
	v_max_f32_e32 v179, v179, v179
	v_max_f32_e32 v179, v179, v255
	v_sub_f32_e32 v255, v179, v175
	v_cmp_ge_f32_e32 vcc, s65, v255
	v_mfma_f32_32x32x16_bf16 v[32:47], v[180:183], v[224:227], v[32:47]
	ds_read_b64_tr_b16 v[224:225], v160 offset:0x1400
	ds_read_b64_tr_b16 v[226:227], v160 offset:0x1c00
	v_max_f32_e32 v255, v175, v175
	v_max_f32_e32 v179, v255, v179
	v_sub_f32_e32 v255, v175, v179
	v_mul_f32_e32 v255, 0x3e38aa3b, v255
	v_exp_f32_e32 v255, v255
	v_mfma_f32_32x32x16_bf16 v[32:47], v[184:187], v[228:231], v[32:47]
	ds_read_b64_tr_b16 v[228:229], v160 offset:0x2400
	ds_read_b64_tr_b16 v[230:231], v160 offset:0x2c00
	s_cmp_eq_u64 vcc, exec
	s_cselect_b64 s[8:9], -1, 0
	v_cndmask_b32_e64 v255, v255, 1.0, s[8:9]
	v_cndmask_b32_e64 v175, v179, v175, s[8:9]
	v_mul_f32_e32 v179, 0xbe38aa3b, v175
	v_mfma_f32_32x32x16_bf16 v[32:47], v[216:219], v[232:235], v[32:47]
	ds_read_b64_tr_b16 v[232:233], v160 offset:0x3400
	ds_read_b64_tr_b16 v[234:235], v160 offset:0x3c00
	v_pk_fma_f32 v[80:81], v[80:81], s[72:73], v[178:179] op_sel:[0,0,1] op_sel_hi:[1,0,1]
	v_pk_fma_f32 v[82:83], v[82:83], s[72:73], v[178:179] op_sel:[0,0,1] op_sel_hi:[1,0,1]
	v_pk_fma_f32 v[84:85], v[84:85], s[72:73], v[178:179] op_sel:[0,0,1] op_sel_hi:[1,0,1]
	v_pk_fma_f32 v[86:87], v[86:87], s[72:73], v[178:179] op_sel:[0,0,1] op_sel_hi:[1,0,1]
	v_pk_fma_f32 v[88:89], v[88:89], s[72:73], v[178:179] op_sel:[0,0,1] op_sel_hi:[1,0,1]
	s_waitcnt lgkmcnt(0)
	v_mfma_f32_32x32x16_bf16 v[16:31], v[212:215], v[220:223], v[16:31]
	ds_read_b64_tr_b16 v[220:221], v160 offset:0x600
	ds_read_b64_tr_b16 v[222:223], v160 offset:0xe00
	v_pk_fma_f32 v[90:91], v[90:91], s[72:73], v[178:179] op_sel:[0,0,1] op_sel_hi:[1,0,1]
	v_pk_fma_f32 v[92:93], v[92:93], s[72:73], v[178:179] op_sel:[0,0,1] op_sel_hi:[1,0,1]
	v_pk_fma_f32 v[94:95], v[94:95], s[72:73], v[178:179] op_sel:[0,0,1] op_sel_hi:[1,0,1]
	v_exp_f32_e32 v127, v80
	v_mfma_f32_32x32x16_bf16 v[16:31], v[180:183], v[224:227], v[16:31]
	ds_read_b64_tr_b16 v[224:225], v160 offset:0x1600
	ds_read_b64_tr_b16 v[226:227], v160 offset:0x1e00
	v_exp_f32_e32 v129, v81
	v_exp_f32_e32 v125, v82
	v_exp_f32_e32 v128, v83
	v_mfma_f32_32x32x16_bf16 v[16:31], v[184:187], v[228:231], v[16:31]
	ds_read_b64_tr_b16 v[228:229], v160 offset:0x2600
	ds_read_b64_tr_b16 v[230:231], v160 offset:0x2e00
	v_exp_f32_e32 v123, v84
	v_exp_f32_e32 v126, v85
	v_exp_f32_e32 v122, v86
	v_mfma_f32_32x32x16_bf16 v[16:31], v[216:219], v[232:235], v[16:31]
	ds_read_b64_tr_b16 v[232:233], v160 offset:0x3600
	ds_read_b64_tr_b16 v[234:235], v160 offset:0x3e00
	v_exp_f32_e32 v124, v87
	v_exp_f32_e32 v119, v88
	v_exp_f32_e32 v121, v89
	s_waitcnt lgkmcnt(0)
	v_mfma_f32_32x32x16_bf16 v[0:15], v[212:215], v[220:223], v[0:15]
	s_barrier
	s_waitcnt vmcnt(0)
	ds_write_b128 v163, v[240:243]
	ds_write_b128 v164, v[206:209]
	ds_write_b128 v161, v[244:247] offset:32768
	ds_write_b128 v162, v[248:251] offset:32768
	v_exp_f32_e32 v117, v90
	v_exp_f32_e32 v120, v91
	v_exp_f32_e32 v115, v92
	v_fmamk_f32 v189, v64, 0x3e38aa3b, v179
	v_fmamk_f32 v211, v65, 0x3e38aa3b, v179
	v_fmamk_f32 v212, v66, 0x3e38aa3b, v179
	v_fmamk_f32 v213, v67, 0x3e38aa3b, v179
	v_fmamk_f32 v214, v68, 0x3e38aa3b, v179
	v_fmamk_f32 v188, v75, 0x3e38aa3b, v179
	v_fmamk_f32 v215, v77, 0x3e38aa3b, v179
	v_mfma_f32_32x32x16_bf16 v[0:15], v[180:183], v[224:227], v[0:15]
	v_exp_f32_e32 v118, v93
	v_exp_f32_e32 v114, v94
	v_exp_f32_e32 v116, v95
	v_fmamk_f32 v182, v69, 0x3e38aa3b, v179
	v_fmamk_f32 v183, v70, 0x3e38aa3b, v179
	v_fmamk_f32 v181, v76, 0x3e38aa3b, v179
	v_mfma_f32_32x32x16_bf16 v[0:15], v[184:187], v[228:231], v[0:15]
	v_fmamk_f32 v184, v71, 0x3e38aa3b, v179
	v_fmamk_f32 v185, v72, 0x3e38aa3b, v179
	v_fmamk_f32 v186, v73, 0x3e38aa3b, v179
	v_fmamk_f32 v187, v74, 0x3e38aa3b, v179
	v_mfma_f32_32x32x16_bf16 v[0:15], v[216:219], v[232:235], v[0:15]
	v_fmamk_f32 v216, v78, 0x3e38aa3b, v179
	v_fmac_f32_e32 v179, 0x3e38aa3b, v79
	v_mov_b32_e32 v180, v255
	s_cmp_lg_u64 s[8:9], 0
	s_cbranch_scc1 .LBB0_266
	s_and_saveexec_b64 s[2:3], s[6:7]
	ds_write_b32 v157, v180 offset:128
	s_or_b64 exec, exec, s[2:3]
	s_waitcnt lgkmcnt(0)
	ds_read_b128 v[240:243], v158 offset:224
	ds_read_b128 v[244:247], v158 offset:192
	ds_read_b128 v[248:251], v158 offset:160
	ds_read_b128 v[206:209], v158 offset:128
	s_waitcnt lgkmcnt(3)
	v_pk_mul_f32 v[62:63], v[62:63], v[242:243]
	s_waitcnt lgkmcnt(2)
	v_pk_mul_f32 v[58:59], v[58:59], v[246:247]
	s_waitcnt lgkmcnt(1)
	v_pk_mul_f32 v[54:55], v[54:55], v[250:251]
	s_waitcnt lgkmcnt(0)
	v_pk_mul_f32 v[50:51], v[50:51], v[208:209]
	v_pk_mul_f32 v[60:61], v[60:61], v[240:241]
	v_pk_mul_f32 v[56:57], v[56:57], v[244:245]
	v_pk_mul_f32 v[52:53], v[52:53], v[248:249]
	v_pk_mul_f32 v[48:49], v[48:49], v[206:207]
	v_pk_mul_f32 v[46:47], v[46:47], v[242:243]
	v_pk_mul_f32 v[42:43], v[42:43], v[246:247]
	v_pk_mul_f32 v[38:39], v[38:39], v[250:251]
	v_pk_mul_f32 v[34:35], v[34:35], v[208:209]
	v_pk_mul_f32 v[44:45], v[44:45], v[240:241]
	v_pk_mul_f32 v[40:41], v[40:41], v[244:245]
	v_pk_mul_f32 v[36:37], v[36:37], v[248:249]
	v_pk_mul_f32 v[32:33], v[32:33], v[206:207]
	v_pk_mul_f32 v[30:31], v[30:31], v[242:243]
	v_pk_mul_f32 v[26:27], v[26:27], v[246:247]
	v_pk_mul_f32 v[22:23], v[22:23], v[250:251]
	v_pk_mul_f32 v[18:19], v[18:19], v[208:209]
	v_pk_mul_f32 v[28:29], v[28:29], v[240:241]
	v_pk_mul_f32 v[24:25], v[24:25], v[244:245]
	v_pk_mul_f32 v[20:21], v[20:21], v[248:249]
	v_pk_mul_f32 v[16:17], v[16:17], v[206:207]
	v_pk_mul_f32 v[14:15], v[14:15], v[242:243]
	v_pk_mul_f32 v[10:11], v[10:11], v[246:247]
	v_pk_mul_f32 v[6:7], v[6:7], v[250:251]
	v_pk_mul_f32 v[2:3], v[2:3], v[208:209]
	v_pk_mul_f32 v[12:13], v[12:13], v[240:241]
	v_pk_mul_f32 v[8:9], v[8:9], v[244:245]
	v_pk_mul_f32 v[4:5], v[4:5], v[248:249]
	v_pk_mul_f32 v[0:1], v[0:1], v[206:207]
; __device__ __forceinline__ void finishSM(f32x16& p0, f32x16& p1, float alpha, float& l_reg, bf16x8& pa0, bf16x8& pa1, bf16x8& pa2, bf16x8& pa3) {
; #pragma unroll
;     for (int r = 0; r < 16; ++r) p1[r] = __builtin_amdgcn_exp2f(p1[r]);
;     float ps = 0;
; #pragma unroll
;     for (int r = 0; r < 16; ++r) ps += p0[r];
; #pragma unroll
;     for (int r = 0; r < 16; ++r) ps += p1[r];
;     { auto rr = __builtin_amdgcn_permlane32_swap(__float_as_uint(ps), __float_as_uint(ps), false, false);
;       ps = __uint_as_float(rr[0]) + __uint_as_float(rr[1]); }
;     l_reg = l_reg * alpha + ps;
;     ...
;     PK4(p0, 0, pa0); PK4(p0, 8, pa1); PK4(p1, 0, pa2); PK4(p1, 8, pa3);
;     ...
; }
; __device__ __forceinline__ void qkt(f32x16& p0, f32x16& p1, const char* Ks, const bf16x8* qr, int r32, int hi, int comp) {
;     p0 = f32x16{}; p1 = f32x16{};
; #pragma unroll
;     for (int d0 = 0; d0 < 4; ++d0) { const int cb = (comp * 64 + d0 * 16 + hi * 8) * 2;
;         const bf16x8 b0 = *reinterpret_cast<const bf16x8*>(Ks + KSWZ(r32, cb));
;         const bf16x8 b1 = *reinterpret_cast<const bf16x8*>(Ks + KSWZ(32 + r32, cb));
;         p0 = __builtin_amdgcn_mfma_f32_32x32x16_bf16(b0, qr[d0], p0, 0, 0, 0);
;         p1 = __builtin_amdgcn_mfma_f32_32x32x16_bf16(b1, qr[d0], p1, 0, 0, 0); }
; }
; __device__ __forceinline__ int v_st(int k, int c) { const int kk = (k & ~0xC) | ((k & 4) << 1) | ((k & 8) >> 1); return ((kk >> 3) * 4 + (c >> 5)) * 512 + ((kk & 7) * 32 + (c & 31)) * 2; }
; __device__ __forceinline__ int v_rd_base(int lane) { return ((lane & 3) << 3) | (((lane >> 2) & 3) << 6) | (((lane >> 4) & 1) << 5) | (((lane >> 5) & 1) << 8); }
; template <int OFF> __device__ __forceinline__ s16x4 tr_read(int vb) {
;     s16x4 r; asm volatile("ds_read_b64_tr_b16 %0, %1 offset:%2" : "=&v"(r) : "v"(vb), "i"(OFF) : "memory"); return r;
; }
; template <int D0> __device__ __forceinline__ void pv_one(f32x16& od, int vb, bf16x8 pa0, bf16x8 pa1, bf16x8 pa2, bf16x8 pa3) {
;     const s16x4 l0 = tr_read<v_rd_off(D0, 0, 0)>(vb), h0 = tr_read<v_rd_off(D0, 0, 1)>(vb), l1 = tr_read<v_rd_off(D0, 1, 0)>(vb), h1 = tr_read<v_rd_off(D0, 1, 1)>(vb);
;     const s16x4 l2 = tr_read<v_rd_off(D0, 2, 0)>(vb), h2 = tr_read<v_rd_off(D0, 2, 1)>(vb), l3 = tr_read<v_rd_off(D0, 3, 0)>(vb), h3 = tr_read<v_rd_off(D0, 3, 1)>(vb);
;     asm volatile("s_waitcnt lgkmcnt(0)" ::: "memory"); SBAR();
.LBB0_266:
	s_waitcnt lgkmcnt(0)
	s_barrier
	ds_read_b128 v[64:67], v170 offset:32768
	ds_read_b128 v[68:71], v170 offset:40960
	v_exp_f32_e32 v203, v181
	v_add_f32_e32 v181, 0, v127
	v_add_f32_e32 v181, v129, v181
	s_waitcnt lgkmcnt(1)
	v_mfma_f32_32x32x16_bf16 v[80:95], v[64:67], v[110:113], 0
	v_add_f32_e32 v181, v125, v181
	v_add_f32_e32 v181, v128, v181
	v_add_f32_e32 v181, v123, v181
	ds_read_b128 v[218:221], v171 offset:32768
	ds_read_b128 v[222:225], v171 offset:40960
	v_add_f32_e32 v181, v126, v181
	v_add_f32_e32 v181, v122, v181
	v_add_f32_e32 v181, v124, v181
	s_waitcnt lgkmcnt(2)
	v_mfma_f32_32x32x16_bf16 v[64:79], v[68:71], v[110:113], 0
	v_add_f32_e32 v181, v119, v181
	v_add_f32_e32 v181, v121, v181
	v_add_f32_e32 v181, v117, v181
	v_add_f32_e32 v181, v120, v181
	v_exp_f32_e32 v189, v189
	v_add_f32_e32 v181, v115, v181
	v_exp_f32_e32 v190, v211
	s_waitcnt lgkmcnt(1)
	v_mfma_f32_32x32x16_bf16 v[80:95], v[218:221], v[106:109], v[80:95]
	v_add_f32_e32 v181, v118, v181
	v_exp_f32_e32 v191, v212
	v_add_f32_e32 v181, v114, v181
	v_exp_f32_e32 v192, v213
	v_add_f32_e32 v181, v116, v181
	v_exp_f32_e32 v193, v214
	v_add_f32_e32 v181, v189, v181
	s_waitcnt lgkmcnt(0)
	v_mfma_f32_32x32x16_bf16 v[64:79], v[222:225], v[106:109], v[64:79]
	ds_read_b128 v[218:221], v173 offset:32768
	ds_read_b128 v[222:225], v173 offset:40960
	v_exp_f32_e32 v194, v182
	v_add_f32_e32 v181, v190, v181
	v_exp_f32_e32 v183, v183
	v_add_f32_e32 v181, v191, v181
	v_exp_f32_e32 v195, v184
	v_add_f32_e32 v181, v192, v181
	s_waitcnt lgkmcnt(1)
	v_mfma_f32_32x32x16_bf16 v[80:95], v[218:221], v[102:105], v[80:95]
	v_exp_f32_e32 v200, v185
	v_add_f32_e32 v181, v193, v181
	v_exp_f32_e32 v201, v186
	v_add_f32_e32 v181, v194, v181
	v_exp_f32_e32 v202, v187
	v_add_f32_e32 v181, v183, v181
	v_exp_f32_e32 v188, v188
	s_waitcnt lgkmcnt(0)
	v_mfma_f32_32x32x16_bf16 v[64:79], v[222:225], v[102:105], v[64:79]
	ds_read_b128 v[218:221], v172 offset:32768
	ds_read_b128 v[222:225], v172 offset:40960
	v_add_f32_e32 v181, v195, v181
	v_add_f32_e32 v181, v200, v181
	v_exp_f32_e32 v204, v215
	v_add_f32_e32 v181, v201, v181
	v_exp_f32_e32 v205, v216
	v_add_f32_e32 v181, v202, v181
	s_waitcnt lgkmcnt(1)
	v_mfma_f32_32x32x16_bf16 v[80:95], v[218:221], v[98:101], v[80:95]
	v_exp_f32_e32 v179, v179
	v_add_f32_e32 v181, v188, v181
	v_add_f32_e32 v181, v203, v181
	v_add_f32_e32 v181, v204, v181
	v_add_f32_e32 v181, v205, v181
	v_add_f32_e32 v181, v179, v181
	v_mov_b32_e32 v182, v181
	s_waitcnt lgkmcnt(0)
	v_mfma_f32_32x32x16_bf16 v[64:79], v[222:225], v[98:101], v[64:79]
	v_permlane32_swap_b32_e32 v181, v182
	v_cvt_pk_bf16_f32 v184, v127, v129
	v_cvt_pk_bf16_f32 v185, v125, v128
	v_cvt_pk_bf16_f32 v186, v123, v126
	v_cvt_pk_bf16_f32 v187, v122, v124
	v_cvt_pk_bf16_f32 v212, v119, v121
	v_cvt_pk_bf16_f32 v213, v117, v120
	v_cvt_pk_bf16_f32 v214, v115, v118
	v_cvt_pk_bf16_f32 v215, v114, v116
	v_cvt_pk_bf16_f32 v216, v189, v190
	v_cvt_pk_bf16_f32 v217, v191, v192
	v_cvt_pk_bf16_f32 v218, v193, v194
	v_cvt_pk_bf16_f32 v219, v183, v195
	v_cvt_pk_bf16_f32 v220, v200, v201
	v_cvt_pk_bf16_f32 v221, v202, v188
	v_cvt_pk_bf16_f32 v222, v203, v204
	v_cvt_pk_bf16_f32 v223, v205, v179
	s_nop 0
	v_permlane32_swap_b32_e32 v184, v186
	v_permlane32_swap_b32_e32 v185, v187
	v_permlane32_swap_b32_e32 v212, v214
	v_permlane32_swap_b32_e32 v213, v215
	v_permlane32_swap_b32_e32 v216, v218
	v_permlane32_swap_b32_e32 v217, v219
	v_permlane32_swap_b32_e32 v220, v222
	v_permlane32_swap_b32_e32 v221, v223
	v_add_u32_e32 v118, 0x20000, v176
	v_add_u32_e32 v122, 0x30000, v176
	global_load_dwordx4 v[114:117], v118, s[58:59]
	s_nop 0
	global_load_dwordx4 v[118:121], v118, s[28:29]
	s_nop 0
	global_load_dwordx4 v[126:129], v122, s[58:59]
	s_nop 0
	global_load_dwordx4 v[122:125], v122, s[28:29]
	ds_read_b64_tr_b16 v[224:225], v159 offset:0
	ds_read_b64_tr_b16 v[226:227], v159 offset:0x800
	ds_read_b64_tr_b16 v[228:229], v159 offset:0x1000
	ds_read_b64_tr_b16 v[230:231], v159 offset:0x1800
	ds_read_b64_tr_b16 v[232:233], v159 offset:0x2000
	ds_read_b64_tr_b16 v[234:235], v159 offset:0x2800
	ds_read_b64_tr_b16 v[236:237], v159 offset:0x3000
	ds_read_b64_tr_b16 v[238:239], v159 offset:0x3800
	s_waitcnt lgkmcnt(0)
	v_mfma_f32_32x32x16_bf16 v[48:63], v[184:187], v[224:227], v[48:63]
	ds_read_b64_tr_b16 v[224:225], v159 offset:0x200
	ds_read_b64_tr_b16 v[226:227], v159 offset:0xa00
	v_max_f32_e32 v255, v81, v81
	v_max_f32_e32 v210, v80, v80
	v_max_f32_e32 v255, v210, v255
	v_max3_f32 v255, v255, v82, v83
	v_max3_f32 v255, v255, v84, v85
	v_mfma_f32_32x32x16_bf16 v[48:63], v[212:215], v[228:231], v[48:63]
	ds_read_b64_tr_b16 v[228:229], v159 offset:0x1200
	ds_read_b64_tr_b16 v[230:231], v159 offset:0x1a00
	v_max3_f32 v255, v255, v86, v87
	v_max3_f32 v255, v255, v88, v89
	v_max3_f32 v255, v255, v90, v91
	v_max3_f32 v255, v255, v92, v93
	v_max3_f32 v255, v255, v94, v95
	v_mfma_f32_32x32x16_bf16 v[48:63], v[216:219], v[232:235], v[48:63]
	ds_read_b64_tr_b16 v[232:233], v159 offset:0x2200
	ds_read_b64_tr_b16 v[234:235], v159 offset:0x2a00
	v_max3_f32 v255, v255, v64, v65
	v_max3_f32 v255, v255, v66, v67
	v_max3_f32 v255, v255, v68, v69
	v_max3_f32 v255, v255, v70, v71
	v_max3_f32 v255, v255, v72, v73
	v_mfma_f32_32x32x16_bf16 v[48:63], v[220:223], v[236:239], v[48:63]
	ds_read_b64_tr_b16 v[236:237], v159 offset:0x3200
	ds_read_b64_tr_b16 v[238:239], v159 offset:0x3a00
	v_max3_f32 v255, v255, v74, v75
	v_max3_f32 v255, v255, v76, v77
	v_max3_f32 v255, v255, v78, v79
	v_mov_b32_e32 v210, v255
	s_nop 1
	v_permlane32_swap_b32_e32 v255, v210
	s_waitcnt lgkmcnt(0)
; __device__ __forceinline__ void partialSM(f32x16& p0, f32x16& p1, float& m_reg, float& mn, float& alpha) {
;     constexpr float C = SCALE * 1.4426950408889634f;
;     float pmax = p0[0];
; #pragma unroll
;     for (int r = 1; r < 16; ++r) pmax = fmaxf(pmax, p0[r]);
; #pragma unroll
;     for (int r = 0; r < 16; ++r) pmax = fmaxf(pmax, p1[r]);
;     { auto rr = __builtin_amdgcn_permlane32_swap(__float_as_uint(pmax), __float_as_uint(pmax), false, false);
;       pmax = fmaxf(__uint_as_float(rr[0]), __uint_as_float(rr[1])); }
;     if (__builtin_expect(__all(pmax - m_reg <= THR / SCALE), 1)) { mn = m_reg; alpha = 1.f; }
;     else { mn = fmaxf(m_reg, pmax); alpha = __builtin_amdgcn_exp2f((m_reg - mn) * C); m_reg = mn; }
;     const float mnC = -mn * C;
; #pragma unroll
;     for (int r = 0; r < 16; ++r) p0[r] = fmaf(p0[r], C, mnC);
; #pragma unroll
;     for (int r = 0; r < 16; ++r) p1[r] = fmaf(p1[r], C, mnC);
; #pragma unroll
;     for (int r = 0; r < 16; ++r) p0[r] = __builtin_amdgcn_exp2f(p0[r]);
; }
	v_mfma_f32_32x32x16_bf16 v[32:47], v[184:187], v[224:227], v[32:47]
	ds_read_b64_tr_b16 v[224:225], v159 offset:0x400
	ds_read_b64_tr_b16 v[226:227], v159 offset:0xc00
	v_max_f32_e32 v210, v210, v210
	v_max_f32_e32 v255, v255, v255
	v_max_f32_e32 v255, v255, v210
	v_sub_f32_e32 v210, v255, v175
	v_cmp_ge_f32_e32 vcc, s65, v210
	v_mfma_f32_32x32x16_bf16 v[32:47], v[212:215], v[228:231], v[32:47]
	ds_read_b64_tr_b16 v[228:229], v159 offset:0x1400
	ds_read_b64_tr_b16 v[230:231], v159 offset:0x1c00
	v_max_f32_e32 v210, v175, v175
	v_max_f32_e32 v210, v210, v255
	v_sub_f32_e32 v255, v175, v210
	v_mul_f32_e32 v255, 0x3e38aa3b, v255
	v_exp_f32_e32 v255, v255
	v_mfma_f32_32x32x16_bf16 v[32:47], v[216:219], v[232:235], v[32:47]
	ds_read_b64_tr_b16 v[232:233], v159 offset:0x2400
	ds_read_b64_tr_b16 v[234:235], v159 offset:0x2c00
	s_cmp_eq_u64 vcc, exec
	s_cselect_b64 s[8:9], -1, 0
	v_cndmask_b32_e64 v255, v255, 1.0, s[8:9]
	v_cndmask_b32_e64 v175, v210, v175, s[8:9]
	v_mul_f32_e32 v210, 0xbe38aa3b, v175
	v_mfma_f32_32x32x16_bf16 v[32:47], v[220:223], v[236:239], v[32:47]
	ds_read_b64_tr_b16 v[236:237], v159 offset:0x3400
	ds_read_b64_tr_b16 v[238:239], v159 offset:0x3c00
	v_pk_fma_f32 v[80:81], v[80:81], s[72:73], v[210:211] op_sel_hi:[1,0,0]
	v_pk_fma_f32 v[82:83], v[82:83], s[72:73], v[210:211] op_sel_hi:[1,0,0]
	v_pk_fma_f32 v[84:85], v[84:85], s[72:73], v[210:211] op_sel_hi:[1,0,0]
	v_pk_fma_f32 v[86:87], v[86:87], s[72:73], v[210:211] op_sel_hi:[1,0,0]
	v_pk_fma_f32 v[88:89], v[88:89], s[72:73], v[210:211] op_sel_hi:[1,0,0]
	s_waitcnt lgkmcnt(0)
	v_mfma_f32_32x32x16_bf16 v[16:31], v[184:187], v[224:227], v[16:31]
	ds_read_b64_tr_b16 v[224:225], v159 offset:0x600
	ds_read_b64_tr_b16 v[226:227], v159 offset:0xe00
	v_pk_fma_f32 v[90:91], v[90:91], s[72:73], v[210:211] op_sel_hi:[1,0,0]
	v_pk_fma_f32 v[92:93], v[92:93], s[72:73], v[210:211] op_sel_hi:[1,0,0]
	v_pk_fma_f32 v[94:95], v[94:95], s[72:73], v[210:211] op_sel_hi:[1,0,0]
	v_exp_f32_e32 v240, v80
	v_mfma_f32_32x32x16_bf16 v[16:31], v[212:215], v[228:231], v[16:31]
	ds_read_b64_tr_b16 v[228:229], v159 offset:0x1600
	ds_read_b64_tr_b16 v[230:231], v159 offset:0x1e00
	v_exp_f32_e32 v241, v81
	v_exp_f32_e32 v242, v82
	v_exp_f32_e32 v243, v83
	v_mfma_f32_32x32x16_bf16 v[16:31], v[216:219], v[232:235], v[16:31]
	ds_read_b64_tr_b16 v[232:233], v159 offset:0x2600
	ds_read_b64_tr_b16 v[234:235], v159 offset:0x2e00
	v_exp_f32_e32 v244, v84
	v_exp_f32_e32 v245, v85
	v_exp_f32_e32 v246, v86
	v_mfma_f32_32x32x16_bf16 v[16:31], v[220:223], v[236:239], v[16:31]
	ds_read_b64_tr_b16 v[236:237], v159 offset:0x3600
	ds_read_b64_tr_b16 v[238:239], v159 offset:0x3e00
	v_exp_f32_e32 v247, v87
	v_exp_f32_e32 v248, v88
	v_exp_f32_e32 v249, v89
	s_waitcnt lgkmcnt(0)
	v_mfma_f32_32x32x16_bf16 v[0:15], v[184:187], v[224:227], v[0:15]
	s_barrier
	s_waitcnt vmcnt(0)
	ds_write_b128 v163, v[114:117] offset:16384
	ds_write_b128 v164, v[126:129] offset:16384
	ds_write_b128 v161, v[118:121] offset:49152
	ds_write_b128 v162, v[122:125] offset:49152
	v_exp_f32_e32 v250, v90
	v_exp_f32_e32 v251, v91
	v_exp_f32_e32 v206, v92
	v_mfma_f32_32x32x16_bf16 v[0:15], v[212:215], v[228:231], v[0:15]
	v_exp_f32_e32 v207, v93
	v_exp_f32_e32 v208, v94
	v_exp_f32_e32 v209, v95
	v_mfma_f32_32x32x16_bf16 v[0:15], v[216:219], v[232:235], v[0:15]
	v_mfma_f32_32x32x16_bf16 v[0:15], v[220:223], v[236:239], v[0:15]
	v_mov_b32_e32 v179, v255
	s_cmp_lg_u64 s[8:9], 0
	s_cbranch_scc1 .LBB0_270
	s_and_saveexec_b64 s[2:3], s[6:7]
	ds_write_b32 v157, v179 offset:128
	s_or_b64 exec, exec, s[2:3]
	s_waitcnt lgkmcnt(0)
	ds_read_b128 v[114:117], v158 offset:224
	ds_read_b128 v[118:121], v158 offset:192
	ds_read_b128 v[122:125], v158 offset:160
	ds_read_b128 v[126:129], v158 offset:128
	s_waitcnt lgkmcnt(3)
	v_pk_mul_f32 v[62:63], v[62:63], v[116:117]
	s_waitcnt lgkmcnt(2)
	v_pk_mul_f32 v[58:59], v[58:59], v[120:121]
	s_waitcnt lgkmcnt(1)
	v_pk_mul_f32 v[54:55], v[54:55], v[124:125]
	s_waitcnt lgkmcnt(0)
	v_pk_mul_f32 v[50:51], v[50:51], v[128:129]
	v_pk_mul_f32 v[60:61], v[60:61], v[114:115]
	v_pk_mul_f32 v[56:57], v[56:57], v[118:119]
	v_pk_mul_f32 v[52:53], v[52:53], v[122:123]
	v_pk_mul_f32 v[48:49], v[48:49], v[126:127]
	v_pk_mul_f32 v[46:47], v[46:47], v[116:117]
	v_pk_mul_f32 v[42:43], v[42:43], v[120:121]
	v_pk_mul_f32 v[38:39], v[38:39], v[124:125]
	v_pk_mul_f32 v[34:35], v[34:35], v[128:129]
	v_pk_mul_f32 v[44:45], v[44:45], v[114:115]
	v_pk_mul_f32 v[40:41], v[40:41], v[118:119]
	v_pk_mul_f32 v[36:37], v[36:37], v[122:123]
	v_pk_mul_f32 v[32:33], v[32:33], v[126:127]
	v_pk_mul_f32 v[30:31], v[30:31], v[116:117]
	v_pk_mul_f32 v[26:27], v[26:27], v[120:121]
	v_pk_mul_f32 v[22:23], v[22:23], v[124:125]
	v_pk_mul_f32 v[18:19], v[18:19], v[128:129]
	v_pk_mul_f32 v[28:29], v[28:29], v[114:115]
	v_pk_mul_f32 v[24:25], v[24:25], v[118:119]
	v_pk_mul_f32 v[20:21], v[20:21], v[122:123]
	v_pk_mul_f32 v[16:17], v[16:17], v[126:127]
	v_pk_mul_f32 v[14:15], v[14:15], v[116:117]
	v_pk_mul_f32 v[10:11], v[10:11], v[120:121]
	v_pk_mul_f32 v[6:7], v[6:7], v[124:125]
	v_pk_mul_f32 v[2:3], v[2:3], v[128:129]
	v_pk_mul_f32 v[12:13], v[12:13], v[114:115]
	v_pk_mul_f32 v[8:9], v[8:9], v[118:119]
	v_pk_mul_f32 v[4:5], v[4:5], v[122:123]
	v_pk_mul_f32 v[0:1], v[0:1], v[126:127]

; __device__ __forceinline__ void finishSM(f32x16& p0, f32x16& p1, float alpha, float& l_reg, bf16x8& pa0, bf16x8& pa1, bf16x8& pa2, bf16x8& pa3) {
; #pragma unroll
;     for (int r = 0; r < 16; ++r) p1[r] = __builtin_amdgcn_exp2f(p1[r]);
;     float ps = 0;
; #pragma unroll
;     for (int r = 0; r < 16; ++r) ps += p0[r];
; #pragma unroll
;     for (int r = 0; r < 16; ++r) ps += p1[r];
;     { auto rr = __builtin_amdgcn_permlane32_swap(__float_as_uint(ps), __float_as_uint(ps), false, false);
;       ps = __uint_as_float(rr[0]) + __uint_as_float(rr[1]); }
;     l_reg = l_reg * alpha + ps;
;     ...
;     PK4(p0, 0, pa0); PK4(p0, 8, pa1); PK4(p1, 0, pa2); PK4(p1, 8, pa3);
;     ...
; }
; __device__ __forceinline__ void qkt(f32x16& p0, f32x16& p1, const char* Ks, const bf16x8* qr, int r32, int hi, int comp) {
;     p0 = f32x16{}; p1 = f32x16{};
; #pragma unroll
;     for (int d0 = 0; d0 < 4; ++d0) { const int cb = (comp * 64 + d0 * 16 + hi * 8) * 2;
;         const bf16x8 b0 = *reinterpret_cast<const bf16x8*>(Ks + KSWZ(r32, cb));
;         const bf16x8 b1 = *reinterpret_cast<const bf16x8*>(Ks + KSWZ(32 + r32, cb));
;         p0 = __builtin_amdgcn_mfma_f32_32x32x16_bf16(b0, qr[d0], p0, 0, 0, 0);
;         p1 = __builtin_amdgcn_mfma_f32_32x32x16_bf16(b1, qr[d0], p1, 0, 0, 0); }
; }
; __device__ __forceinline__ int v_st(int k, int c) { const int kk = (k & ~0xC) | ((k & 4) << 1) | ((k & 8) >> 1); return ((kk >> 3) * 4 + (c >> 5)) * 512 + ((kk & 7) * 32 + (c & 31)) * 2; }
; __device__ __forceinline__ int v_rd_base(int lane) { return ((lane & 3) << 3) | (((lane >> 2) & 3) << 6) | (((lane >> 4) & 1) << 5) | (((lane >> 5) & 1) << 8); }
; template <int OFF> __device__ __forceinline__ s16x4 tr_read(int vb) {
;     s16x4 r; asm volatile("ds_read_b64_tr_b16 %0, %1 offset:%2" : "=&v"(r) : "v"(vb), "i"(OFF) : "memory"); return r;
; }
; template <int D0> __device__ __forceinline__ void pv_one(f32x16& od, int vb, bf16x8 pa0, bf16x8 pa1, bf16x8 pa2, bf16x8 pa3) {
;     const s16x4 l0 = tr_read<v_rd_off(D0, 0, 0)>(vb), h0 = tr_read<v_rd_off(D0, 0, 1)>(vb), l1 = tr_read<v_rd_off(D0, 1, 0)>(vb), h1 = tr_read<v_rd_off(D0, 1, 1)>(vb);
;     const s16x4 l2 = tr_read<v_rd_off(D0, 2, 0)>(vb), h2 = tr_read<v_rd_off(D0, 2, 1)>(vb), l3 = tr_read<v_rd_off(D0, 3, 0)>(vb), h3 = tr_read<v_rd_off(D0, 3, 1)>(vb);
;     asm volatile("s_waitcnt lgkmcnt(0)" ::: "memory"); SBAR();
.LBB0_280:
	ds_read_b128 v[64:67], v140 offset:49152
	ds_read_b128 v[68:71], v140 offset:57344
	v_add_f32_e32 v135, 0, v240
	v_add_f32_e32 v135, v241, v135
	v_add_f32_e32 v135, v242, v135
	s_waitcnt lgkmcnt(1)
	v_mfma_f32_32x32x16_bf16 v[80:95], v[64:67], v[110:113], 0
	v_add_f32_e32 v135, v243, v135
	v_add_f32_e32 v135, v244, v135
	ds_read_b128 v[136:139], v143 offset:49152
	ds_read_b128 v[178:181], v143 offset:57344
	v_add_f32_e32 v135, v245, v135
	v_add_f32_e32 v135, v246, v135
	v_add_f32_e32 v135, v247, v135
	v_add_f32_e32 v135, v248, v135
	s_waitcnt lgkmcnt(2)
	v_mfma_f32_32x32x16_bf16 v[64:79], v[68:71], v[110:113], 0
	v_add_f32_e32 v135, v249, v135
	v_add_f32_e32 v135, v250, v135
	v_add_f32_e32 v135, v251, v135
	v_exp_f32_e32 v128, v128
	v_add_f32_e32 v135, v206, v135
	v_exp_f32_e32 v129, v129
	v_add_f32_e32 v135, v207, v135
	s_waitcnt lgkmcnt(1)
	v_mfma_f32_32x32x16_bf16 v[80:95], v[136:139], v[106:109], v[80:95]
	v_exp_f32_e32 v126, v126
	v_add_f32_e32 v135, v208, v135
	v_exp_f32_e32 v127, v127
	v_add_f32_e32 v135, v209, v135
	v_exp_f32_e32 v122, v122
	v_add_f32_e32 v135, v128, v135
	v_exp_f32_e32 v123, v123
	s_waitcnt lgkmcnt(0)
	v_mfma_f32_32x32x16_bf16 v[64:79], v[178:181], v[106:109], v[64:79]
	ds_read_b128 v[136:139], v142 offset:49152
	ds_read_b128 v[178:181], v142 offset:57344
	v_add_f32_e32 v135, v129, v135
	v_exp_f32_e32 v118, v118
	v_add_f32_e32 v135, v126, v135
	v_exp_f32_e32 v119, v119
	v_add_f32_e32 v135, v127, v135
	v_exp_f32_e32 v116, v116
	s_waitcnt lgkmcnt(1)
	v_mfma_f32_32x32x16_bf16 v[80:95], v[136:139], v[102:105], v[80:95]
	v_add_f32_e32 v135, v122, v135
	v_exp_f32_e32 v117, v117
	v_add_f32_e32 v135, v123, v135
	v_exp_f32_e32 v124, v124
	v_add_f32_e32 v135, v118, v135
	v_exp_f32_e32 v125, v125
	v_add_f32_e32 v135, v119, v135
	s_waitcnt lgkmcnt(0)
	v_mfma_f32_32x32x16_bf16 v[64:79], v[178:181], v[102:105], v[64:79]
	ds_read_b128 v[136:139], v141 offset:49152
	ds_read_b128 v[178:181], v141 offset:57344
	v_exp_f32_e32 v120, v120
	v_add_f32_e32 v135, v116, v135
	v_exp_f32_e32 v121, v121
	v_add_f32_e32 v135, v117, v135
	v_exp_f32_e32 v114, v114
	v_add_f32_e32 v135, v124, v135
	s_waitcnt lgkmcnt(1)
	v_mfma_f32_32x32x16_bf16 v[80:95], v[136:139], v[98:101], v[80:95]
	v_exp_f32_e32 v115, v115
	v_add_f32_e32 v135, v125, v135
	v_add_f32_e32 v135, v120, v135
	v_add_f32_e32 v135, v121, v135
	v_add_f32_e32 v135, v114, v135
	v_add_f32_e32 v135, v115, v135
	v_mov_b32_e32 v136, v135
	s_waitcnt lgkmcnt(0)
	v_mfma_f32_32x32x16_bf16 v[64:79], v[178:181], v[98:101], v[64:79]
	v_permlane32_swap_b32_e32 v135, v136
	v_cvt_pk_bf16_f32 v178, v240, v241
	v_cvt_pk_bf16_f32 v179, v242, v243
	v_cvt_pk_bf16_f32 v180, v244, v245
	v_cvt_pk_bf16_f32 v181, v246, v247
	v_cvt_pk_bf16_f32 v144, v248, v249
	v_cvt_pk_bf16_f32 v145, v250, v251
	v_cvt_pk_bf16_f32 v146, v206, v207
	v_cvt_pk_bf16_f32 v147, v208, v209
	v_cvt_pk_bf16_f32 v166, v128, v129
	v_cvt_pk_bf16_f32 v167, v126, v127
	v_cvt_pk_bf16_f32 v168, v122, v123
	v_cvt_pk_bf16_f32 v169, v118, v119
	v_cvt_pk_bf16_f32 v170, v116, v117
	v_cvt_pk_bf16_f32 v171, v124, v125
	v_cvt_pk_bf16_f32 v172, v120, v121
	v_cvt_pk_bf16_f32 v173, v114, v115
	s_nop 0
	v_permlane32_swap_b32_e32 v178, v180
	v_permlane32_swap_b32_e32 v179, v181
	v_permlane32_swap_b32_e32 v144, v146
	v_permlane32_swap_b32_e32 v145, v147
	v_permlane32_swap_b32_e32 v166, v168
	v_permlane32_swap_b32_e32 v167, v169
	v_permlane32_swap_b32_e32 v170, v172
	v_permlane32_swap_b32_e32 v171, v173
	v_add_u32_e32 v122, 0x10000, v96
	global_load_dwordx4 v[240:243], v96, s[58:59]
	global_load_dwordx4 v[244:247], v96, s[28:29]
	global_load_dwordx4 v[206:209], v122, s[58:59]
	s_nop 0
	global_load_dwordx4 v[248:251], v122, s[28:29]
	ds_read_b64_tr_b16 v[174:175], v160 offset:0
	ds_read_b64_tr_b16 v[176:177], v160 offset:0x800
	ds_read_b64_tr_b16 v[182:183], v160 offset:0x1000
	ds_read_b64_tr_b16 v[184:185], v160 offset:0x1800
	ds_read_b64_tr_b16 v[186:187], v160 offset:0x2000
	ds_read_b64_tr_b16 v[188:189], v160 offset:0x2800
	ds_read_b64_tr_b16 v[212:213], v160 offset:0x3000
	ds_read_b64_tr_b16 v[214:215], v160 offset:0x3800
	s_waitcnt lgkmcnt(0)
	v_mfma_f32_32x32x16_bf16 v[48:63], v[178:181], v[174:177], v[48:63]
	ds_read_b64_tr_b16 v[174:175], v160 offset:0x200
	ds_read_b64_tr_b16 v[176:177], v160 offset:0xa00
	v_max_f32_e32 v137, v81, v81
	v_max_f32_e32 v138, v80, v80
	v_max_f32_e32 v137, v138, v137
	v_max3_f32 v137, v137, v82, v83
	v_max3_f32 v137, v137, v84, v85
	v_mfma_f32_32x32x16_bf16 v[48:63], v[144:147], v[182:185], v[48:63]
	ds_read_b64_tr_b16 v[182:183], v160 offset:0x1200
	ds_read_b64_tr_b16 v[184:185], v160 offset:0x1a00
	v_max3_f32 v137, v137, v86, v87
	v_max3_f32 v137, v137, v88, v89
	v_max3_f32 v137, v137, v90, v91
	v_max3_f32 v137, v137, v92, v93
	v_max3_f32 v137, v137, v94, v95
	v_mfma_f32_32x32x16_bf16 v[48:63], v[166:169], v[186:189], v[48:63]
	ds_read_b64_tr_b16 v[186:187], v160 offset:0x2200
	ds_read_b64_tr_b16 v[188:189], v160 offset:0x2a00
	v_max3_f32 v137, v137, v64, v65
	v_max3_f32 v137, v137, v66, v67
	v_max3_f32 v137, v137, v68, v69
	v_max3_f32 v137, v137, v70, v71
	v_max3_f32 v137, v137, v72, v73
	v_mfma_f32_32x32x16_bf16 v[48:63], v[170:173], v[212:215], v[48:63]
	ds_read_b64_tr_b16 v[212:213], v160 offset:0x3200
	ds_read_b64_tr_b16 v[214:215], v160 offset:0x3a00
	v_max3_f32 v137, v137, v74, v75
	v_max3_f32 v137, v137, v76, v77
	v_max3_f32 v137, v137, v78, v79
	v_mov_b32_e32 v138, v137
	s_nop 1
	v_permlane32_swap_b32_e32 v137, v138
	s_waitcnt lgkmcnt(0)
; __device__ __forceinline__ void partialSM(f32x16& p0, f32x16& p1, float& m_reg, float& mn, float& alpha) {
;     constexpr float C = SCALE * 1.4426950408889634f;
;     float pmax = p0[0];
; #pragma unroll
;     for (int r = 1; r < 16; ++r) pmax = fmaxf(pmax, p0[r]);
; #pragma unroll
;     for (int r = 0; r < 16; ++r) pmax = fmaxf(pmax, p1[r]);
;     { auto rr = __builtin_amdgcn_permlane32_swap(__float_as_uint(pmax), __float_as_uint(pmax), false, false);
;       pmax = fmaxf(__uint_as_float(rr[0]), __uint_as_float(rr[1])); }
;     if (__builtin_expect(__all(pmax - m_reg <= THR / SCALE), 1)) { mn = m_reg; alpha = 1.f; }
;     else { mn = fmaxf(m_reg, pmax); alpha = __builtin_amdgcn_exp2f((m_reg - mn) * C); m_reg = mn; }
;     const float mnC = -mn * C;
; #pragma unroll
;     for (int r = 0; r < 16; ++r) p0[r] = fmaf(p0[r], C, mnC);
; #pragma unroll
;     for (int r = 0; r < 16; ++r) p1[r] = fmaf(p1[r], C, mnC);
; #pragma unroll
;     for (int r = 0; r < 16; ++r) p0[r] = __builtin_amdgcn_exp2f(p0[r]);
; }
	v_mfma_f32_32x32x16_bf16 v[32:47], v[178:181], v[174:177], v[32:47]
	ds_read_b64_tr_b16 v[174:175], v160 offset:0x400
	ds_read_b64_tr_b16 v[176:177], v160 offset:0xc00
	v_max_f32_e32 v138, v138, v138
	v_max_f32_e32 v137, v137, v137
	v_max_f32_e32 v137, v137, v138
	v_sub_f32_e32 v138, v137, v134
	v_cmp_ge_f32_e32 vcc, s65, v138
	v_mfma_f32_32x32x16_bf16 v[32:47], v[144:147], v[182:185], v[32:47]
	ds_read_b64_tr_b16 v[182:183], v160 offset:0x1400
	ds_read_b64_tr_b16 v[184:185], v160 offset:0x1c00
	v_max_f32_e32 v138, v134, v134
	v_max_f32_e32 v137, v138, v137
	v_sub_f32_e32 v138, v134, v137
	v_mul_f32_e32 v138, 0x3e38aa3b, v138
	v_exp_f32_e32 v138, v138
	v_mfma_f32_32x32x16_bf16 v[32:47], v[166:169], v[186:189], v[32:47]
	ds_read_b64_tr_b16 v[186:187], v160 offset:0x2400
	ds_read_b64_tr_b16 v[188:189], v160 offset:0x2c00
	s_cmp_eq_u64 vcc, exec
	s_cselect_b64 s[8:9], -1, 0
	v_cndmask_b32_e64 v138, v138, 1.0, s[8:9]
	v_cndmask_b32_e64 v134, v137, v134, s[8:9]
	v_mul_f32_e32 v137, 0xbe38aa3b, v134
	v_mfma_f32_32x32x16_bf16 v[32:47], v[170:173], v[212:215], v[32:47]
	ds_read_b64_tr_b16 v[212:213], v160 offset:0x3400
	ds_read_b64_tr_b16 v[214:215], v160 offset:0x3c00
	v_pk_fma_f32 v[80:81], v[80:81], s[72:73], v[136:137] op_sel:[0,0,1] op_sel_hi:[1,0,1]
	v_pk_fma_f32 v[82:83], v[82:83], s[72:73], v[136:137] op_sel:[0,0,1] op_sel_hi:[1,0,1]
	v_pk_fma_f32 v[84:85], v[84:85], s[72:73], v[136:137] op_sel:[0,0,1] op_sel_hi:[1,0,1]
	v_pk_fma_f32 v[86:87], v[86:87], s[72:73], v[136:137] op_sel:[0,0,1] op_sel_hi:[1,0,1]
	v_pk_fma_f32 v[88:89], v[88:89], s[72:73], v[136:137] op_sel:[0,0,1] op_sel_hi:[1,0,1]
	s_waitcnt lgkmcnt(0)
	v_mfma_f32_32x32x16_bf16 v[16:31], v[178:181], v[174:177], v[16:31]
	ds_read_b64_tr_b16 v[174:175], v160 offset:0x600
	ds_read_b64_tr_b16 v[176:177], v160 offset:0xe00
	v_pk_fma_f32 v[90:91], v[90:91], s[72:73], v[136:137] op_sel:[0,0,1] op_sel_hi:[1,0,1]
	v_pk_fma_f32 v[92:93], v[92:93], s[72:73], v[136:137] op_sel:[0,0,1] op_sel_hi:[1,0,1]
	v_pk_fma_f32 v[94:95], v[94:95], s[72:73], v[136:137] op_sel:[0,0,1] op_sel_hi:[1,0,1]
	v_exp_f32_e32 v127, v80
	v_mfma_f32_32x32x16_bf16 v[16:31], v[144:147], v[182:185], v[16:31]
	ds_read_b64_tr_b16 v[182:183], v160 offset:0x1600
	ds_read_b64_tr_b16 v[184:185], v160 offset:0x1e00
	v_exp_f32_e32 v129, v81
	v_exp_f32_e32 v125, v82
	v_exp_f32_e32 v128, v83
	v_mfma_f32_32x32x16_bf16 v[16:31], v[166:169], v[186:189], v[16:31]
	ds_read_b64_tr_b16 v[186:187], v160 offset:0x2600
	ds_read_b64_tr_b16 v[188:189], v160 offset:0x2e00
	v_exp_f32_e32 v123, v84
	v_exp_f32_e32 v126, v85
	v_exp_f32_e32 v122, v86
	v_mfma_f32_32x32x16_bf16 v[16:31], v[170:173], v[212:215], v[16:31]
	ds_read_b64_tr_b16 v[212:213], v160 offset:0x3600
	ds_read_b64_tr_b16 v[214:215], v160 offset:0x3e00
	v_exp_f32_e32 v124, v87
	v_exp_f32_e32 v119, v88
	v_exp_f32_e32 v121, v89
	s_waitcnt lgkmcnt(0)
	v_mfma_f32_32x32x16_bf16 v[0:15], v[178:181], v[174:177], v[0:15]
	s_barrier
	s_waitcnt vmcnt(0)
	ds_write_b128 v163, v[240:243]
	ds_write_b128 v164, v[206:209]
	ds_write_b128 v161, v[244:247] offset:32768
	ds_write_b128 v162, v[248:251] offset:32768
	v_exp_f32_e32 v117, v90
	v_exp_f32_e32 v120, v91
	v_exp_f32_e32 v115, v92
	v_fmamk_f32 v148, v73, 0x3e38aa3b, v137
	v_fmamk_f32 v149, v74, 0x3e38aa3b, v137
	v_fmamk_f32 v139, v76, 0x3e38aa3b, v137
	v_mfma_f32_32x32x16_bf16 v[0:15], v[144:147], v[182:185], v[0:15]
	v_exp_f32_e32 v118, v93
	v_exp_f32_e32 v114, v94
	v_exp_f32_e32 v116, v95
	v_fmamk_f32 v144, v69, 0x3e38aa3b, v137
	v_fmamk_f32 v145, v70, 0x3e38aa3b, v137
	v_fmamk_f32 v146, v71, 0x3e38aa3b, v137
	v_fmamk_f32 v147, v72, 0x3e38aa3b, v137
	v_mfma_f32_32x32x16_bf16 v[0:15], v[166:169], v[186:189], v[0:15]
	v_fmamk_f32 v167, v64, 0x3e38aa3b, v137
	v_fmamk_f32 v168, v65, 0x3e38aa3b, v137
	v_fmamk_f32 v169, v66, 0x3e38aa3b, v137
	v_fmamk_f32 v166, v75, 0x3e38aa3b, v137
	v_mfma_f32_32x32x16_bf16 v[0:15], v[170:173], v[212:215], v[0:15]
	v_fmamk_f32 v170, v67, 0x3e38aa3b, v137
	v_fmamk_f32 v171, v68, 0x3e38aa3b, v137
	v_fmamk_f32 v172, v77, 0x3e38aa3b, v137
	v_fmamk_f32 v173, v78, 0x3e38aa3b, v137
	v_fmac_f32_e32 v137, 0x3e38aa3b, v79
	s_cmp_lg_u64 s[8:9], 0
	s_cbranch_scc1 .LBB0_284
	s_and_saveexec_b64 s[2:3], s[6:7]
	ds_write_b32 v157, v138 offset:128
	s_or_b64 exec, exec, s[2:3]
	s_waitcnt lgkmcnt(0)
	ds_read_b128 v[240:243], v158 offset:224
	ds_read_b128 v[244:247], v158 offset:192
	ds_read_b128 v[248:251], v158 offset:160
	ds_read_b128 v[206:209], v158 offset:128
	s_waitcnt lgkmcnt(3)
	v_pk_mul_f32 v[62:63], v[62:63], v[242:243]
	s_waitcnt lgkmcnt(2)
	v_pk_mul_f32 v[58:59], v[58:59], v[246:247]
	s_waitcnt lgkmcnt(1)
	v_pk_mul_f32 v[54:55], v[54:55], v[250:251]
	s_waitcnt lgkmcnt(0)
	v_pk_mul_f32 v[50:51], v[50:51], v[208:209]
	v_pk_mul_f32 v[60:61], v[60:61], v[240:241]
	v_pk_mul_f32 v[56:57], v[56:57], v[244:245]
	v_pk_mul_f32 v[52:53], v[52:53], v[248:249]
	v_pk_mul_f32 v[48:49], v[48:49], v[206:207]
	v_pk_mul_f32 v[46:47], v[46:47], v[242:243]
	v_pk_mul_f32 v[42:43], v[42:43], v[246:247]
	v_pk_mul_f32 v[38:39], v[38:39], v[250:251]
	v_pk_mul_f32 v[34:35], v[34:35], v[208:209]
	v_pk_mul_f32 v[44:45], v[44:45], v[240:241]
	v_pk_mul_f32 v[40:41], v[40:41], v[244:245]
	v_pk_mul_f32 v[36:37], v[36:37], v[248:249]
	v_pk_mul_f32 v[32:33], v[32:33], v[206:207]
	v_pk_mul_f32 v[30:31], v[30:31], v[242:243]
	v_pk_mul_f32 v[26:27], v[26:27], v[246:247]
	v_pk_mul_f32 v[22:23], v[22:23], v[250:251]
	v_pk_mul_f32 v[18:19], v[18:19], v[208:209]
	v_pk_mul_f32 v[28:29], v[28:29], v[240:241]
	v_pk_mul_f32 v[24:25], v[24:25], v[244:245]
	v_pk_mul_f32 v[20:21], v[20:21], v[248:249]
	v_pk_mul_f32 v[16:17], v[16:17], v[206:207]
	v_pk_mul_f32 v[14:15], v[14:15], v[242:243]
	v_pk_mul_f32 v[10:11], v[10:11], v[246:247]
	v_pk_mul_f32 v[6:7], v[6:7], v[250:251]
	v_pk_mul_f32 v[2:3], v[2:3], v[208:209]
	v_pk_mul_f32 v[12:13], v[12:13], v[240:241]
	v_pk_mul_f32 v[8:9], v[8:9], v[244:245]
	v_pk_mul_f32 v[4:5], v[4:5], v[248:249]
	v_pk_mul_f32 v[0:1], v[0:1], v[206:207]
; __device__ __forceinline__ void finishSM(f32x16& p0, f32x16& p1, float alpha, float& l_reg, bf16x8& pa0, bf16x8& pa1, bf16x8& pa2, bf16x8& pa3) {
; #pragma unroll
;     for (int r = 0; r < 16; ++r) p1[r] = __builtin_amdgcn_exp2f(p1[r]);
;     float ps = 0;
; #pragma unroll
;     for (int r = 0; r < 16; ++r) ps += p0[r];
; #pragma unroll
;     for (int r = 0; r < 16; ++r) ps += p1[r];
;     { auto rr = __builtin_amdgcn_permlane32_swap(__float_as_uint(ps), __float_as_uint(ps), false, false);
;       ps = __uint_as_float(rr[0]) + __uint_as_float(rr[1]); }
;     l_reg = l_reg * alpha + ps;
;     ...
;     PK4(p0, 0, pa0); PK4(p0, 8, pa1); PK4(p1, 0, pa2); PK4(p1, 8, pa3);
;     ...
; }
; __device__ __forceinline__ void qkt(f32x16& p0, f32x16& p1, const char* Ks, const bf16x8* qr, int r32, int hi, int comp) {
;     p0 = f32x16{}; p1 = f32x16{};
; #pragma unroll
;     for (int d0 = 0; d0 < 4; ++d0) { const int cb = (comp * 64 + d0 * 16 + hi * 8) * 2;
;         const bf16x8 b0 = *reinterpret_cast<const bf16x8*>(Ks + KSWZ(r32, cb));
;         const bf16x8 b1 = *reinterpret_cast<const bf16x8*>(Ks + KSWZ(32 + r32, cb));
;         p0 = __builtin_amdgcn_mfma_f32_32x32x16_bf16(b0, qr[d0], p0, 0, 0, 0);
;         p1 = __builtin_amdgcn_mfma_f32_32x32x16_bf16(b1, qr[d0], p1, 0, 0, 0); }
; }
; __device__ __forceinline__ int v_st(int k, int c) { const int kk = (k & ~0xC) | ((k & 4) << 1) | ((k & 8) >> 1); return ((kk >> 3) * 4 + (c >> 5)) * 512 + ((kk & 7) * 32 + (c & 31)) * 2; }
; __device__ __forceinline__ int v_rd_base(int lane) { return ((lane & 3) << 3) | (((lane >> 2) & 3) << 6) | (((lane >> 4) & 1) << 5) | (((lane >> 5) & 1) << 8); }
; template <int OFF> __device__ __forceinline__ s16x4 tr_read(int vb) {
;     s16x4 r; asm volatile("ds_read_b64_tr_b16 %0, %1 offset:%2" : "=&v"(r) : "v"(vb), "i"(OFF) : "memory"); return r;
; }
; template <int D0> __device__ __forceinline__ void pv_one(f32x16& od, int vb, bf16x8 pa0, bf16x8 pa1, bf16x8 pa2, bf16x8 pa3) {
;     const s16x4 l0 = tr_read<v_rd_off(D0, 0, 0)>(vb), h0 = tr_read<v_rd_off(D0, 0, 1)>(vb), l1 = tr_read<v_rd_off(D0, 1, 0)>(vb), h1 = tr_read<v_rd_off(D0, 1, 1)>(vb);
;     const s16x4 l2 = tr_read<v_rd_off(D0, 2, 0)>(vb), h2 = tr_read<v_rd_off(D0, 2, 1)>(vb), l3 = tr_read<v_rd_off(D0, 3, 0)>(vb), h3 = tr_read<v_rd_off(D0, 3, 1)>(vb);
;     asm volatile("s_waitcnt lgkmcnt(0)" ::: "memory"); SBAR();
.LBB0_284:
	s_waitcnt lgkmcnt(0)
	s_barrier
	ds_read_b128 v[64:67], v140 offset:32768
	ds_read_b128 v[68:71], v140 offset:40960
	ds_read_b128 v[174:177], v143 offset:32768
	ds_read_b128 v[178:181], v143 offset:40960
	v_exp_f32_e32 v185, v139
	v_add_f32_e32 v139, 0, v127
	s_waitcnt lgkmcnt(3)
	v_mfma_f32_32x32x16_bf16 v[80:95], v[64:67], v[110:113], 0
	v_add_f32_e32 v139, v129, v139
	v_add_f32_e32 v139, v125, v139
	v_add_f32_e32 v139, v128, v139
	v_add_f32_e32 v139, v123, v139
	v_add_f32_e32 v139, v126, v139
	v_add_f32_e32 v139, v122, v139
	v_add_f32_e32 v139, v124, v139
	s_waitcnt lgkmcnt(2)
	v_mfma_f32_32x32x16_bf16 v[64:79], v[68:71], v[110:113], 0
	v_add_f32_e32 v139, v119, v139
	v_add_f32_e32 v139, v121, v139
	v_add_f32_e32 v139, v117, v139
	v_add_f32_e32 v139, v120, v139
	v_add_f32_e32 v139, v115, v139
	v_add_f32_e32 v139, v118, v139
	v_add_f32_e32 v139, v114, v139
	s_waitcnt lgkmcnt(1)
	v_mfma_f32_32x32x16_bf16 v[80:95], v[174:177], v[106:109], v[80:95]
	v_add_f32_e32 v139, v116, v139
	v_exp_f32_e32 v145, v145
	v_exp_f32_e32 v182, v148
	v_exp_f32_e32 v183, v149
	v_exp_f32_e32 v184, v166
	v_exp_f32_e32 v186, v172
	v_exp_f32_e32 v187, v173
	s_waitcnt lgkmcnt(0)
	v_mfma_f32_32x32x16_bf16 v[64:79], v[178:181], v[106:109], v[64:79]
	ds_read_b128 v[174:177], v142 offset:32768
	ds_read_b128 v[178:181], v142 offset:40960
	v_exp_f32_e32 v137, v137
	s_waitcnt lgkmcnt(1)
	v_mfma_f32_32x32x16_bf16 v[80:95], v[174:177], v[102:105], v[80:95]
	s_waitcnt lgkmcnt(0)
	v_mfma_f32_32x32x16_bf16 v[64:79], v[178:181], v[102:105], v[64:79]
	ds_read_b128 v[174:177], v141 offset:32768
	ds_read_b128 v[178:181], v141 offset:40960
	s_waitcnt lgkmcnt(1)
	v_mfma_f32_32x32x16_bf16 v[80:95], v[174:177], v[98:101], v[80:95]
	v_exp_f32_e32 v174, v167
	v_exp_f32_e32 v175, v168
	v_exp_f32_e32 v176, v169
	v_exp_f32_e32 v177, v170
	v_add_f32_e32 v139, v174, v139
	v_add_f32_e32 v139, v175, v139
	v_add_f32_e32 v139, v176, v139
	s_waitcnt lgkmcnt(0)
	v_mfma_f32_32x32x16_bf16 v[64:79], v[178:181], v[98:101], v[64:79]
	v_exp_f32_e32 v178, v171
	v_exp_f32_e32 v179, v144
	v_exp_f32_e32 v180, v146
	v_add_f32_e32 v139, v177, v139
	v_exp_f32_e32 v181, v147
	v_add_f32_e32 v139, v178, v139
	v_add_f32_e32 v139, v179, v139
	v_add_f32_e32 v139, v145, v139
	v_add_f32_e32 v139, v180, v139
	v_add_f32_e32 v139, v181, v139
	v_add_f32_e32 v139, v182, v139
	v_add_f32_e32 v139, v183, v139
	v_add_f32_e32 v139, v184, v139
	v_add_f32_e32 v139, v185, v139
	v_add_f32_e32 v139, v186, v139
	v_add_f32_e32 v139, v187, v139
	v_add_f32_e32 v139, v137, v139
	v_mov_b32_e32 v144, v139
	s_nop 1
	v_permlane32_swap_b32_e32 v139, v144
	v_cvt_pk_bf16_f32 v146, v127, v129
	v_cvt_pk_bf16_f32 v147, v125, v128
	v_cvt_pk_bf16_f32 v148, v123, v126
	v_cvt_pk_bf16_f32 v149, v122, v124
	v_cvt_pk_bf16_f32 v166, v119, v121
	v_cvt_pk_bf16_f32 v167, v117, v120
	v_cvt_pk_bf16_f32 v168, v115, v118
	v_cvt_pk_bf16_f32 v169, v114, v116
	v_cvt_pk_bf16_f32 v170, v174, v175
	v_cvt_pk_bf16_f32 v171, v176, v177
	v_cvt_pk_bf16_f32 v172, v178, v179
	v_cvt_pk_bf16_f32 v173, v145, v180
	v_cvt_pk_bf16_f32 v174, v181, v182
	v_cvt_pk_bf16_f32 v175, v183, v184
	v_cvt_pk_bf16_f32 v176, v185, v186
	v_cvt_pk_bf16_f32 v177, v187, v137
	s_nop 0
	v_permlane32_swap_b32_e32 v146, v148
	v_permlane32_swap_b32_e32 v147, v149
	v_permlane32_swap_b32_e32 v166, v168
	v_permlane32_swap_b32_e32 v167, v169
	v_permlane32_swap_b32_e32 v170, v172
	v_permlane32_swap_b32_e32 v171, v173
	v_permlane32_swap_b32_e32 v174, v176
	v_permlane32_swap_b32_e32 v175, v177
	v_add_u32_e32 v118, 0x20000, v96
	v_add_u32_e32 v122, 0x30000, v96
	global_load_dwordx4 v[114:117], v118, s[58:59]
	s_nop 0
	global_load_dwordx4 v[118:121], v118, s[28:29]
	s_nop 0
	global_load_dwordx4 v[126:129], v122, s[58:59]
	s_nop 0
	global_load_dwordx4 v[122:125], v122, s[28:29]
	ds_read_b64_tr_b16 v[178:179], v159 offset:0
	ds_read_b64_tr_b16 v[180:181], v159 offset:0x800
	ds_read_b64_tr_b16 v[182:183], v159 offset:0x1000
	ds_read_b64_tr_b16 v[184:185], v159 offset:0x1800
	ds_read_b64_tr_b16 v[186:187], v159 offset:0x2000
	ds_read_b64_tr_b16 v[188:189], v159 offset:0x2800
	ds_read_b64_tr_b16 v[212:213], v159 offset:0x3000
	ds_read_b64_tr_b16 v[214:215], v159 offset:0x3800
	s_waitcnt lgkmcnt(0)
	v_mfma_f32_32x32x16_bf16 v[48:63], v[146:149], v[178:181], v[48:63]
	ds_read_b64_tr_b16 v[178:179], v159 offset:0x200
	ds_read_b64_tr_b16 v[180:181], v159 offset:0xa00
	v_max_f32_e32 v255, v81, v81
	v_max_f32_e32 v210, v80, v80
	v_max_f32_e32 v255, v210, v255
	v_max3_f32 v255, v255, v82, v83
	v_max3_f32 v255, v255, v84, v85
	v_mfma_f32_32x32x16_bf16 v[48:63], v[166:169], v[182:185], v[48:63]
	ds_read_b64_tr_b16 v[182:183], v159 offset:0x1200
	ds_read_b64_tr_b16 v[184:185], v159 offset:0x1a00
	v_max3_f32 v255, v255, v86, v87
	v_max3_f32 v255, v255, v88, v89
	v_max3_f32 v255, v255, v90, v91
	v_max3_f32 v255, v255, v92, v93
	v_max3_f32 v255, v255, v94, v95
	v_mfma_f32_32x32x16_bf16 v[48:63], v[170:173], v[186:189], v[48:63]
	ds_read_b64_tr_b16 v[186:187], v159 offset:0x2200
	ds_read_b64_tr_b16 v[188:189], v159 offset:0x2a00
	v_max3_f32 v255, v255, v64, v65
	v_max3_f32 v255, v255, v66, v67
	v_max3_f32 v255, v255, v68, v69
	v_max3_f32 v255, v255, v70, v71
	v_max3_f32 v255, v255, v72, v73
	v_mfma_f32_32x32x16_bf16 v[48:63], v[174:177], v[212:215], v[48:63]
	ds_read_b64_tr_b16 v[212:213], v159 offset:0x3200
	ds_read_b64_tr_b16 v[214:215], v159 offset:0x3a00
	v_max3_f32 v255, v255, v74, v75
	v_max3_f32 v255, v255, v76, v77
	v_max3_f32 v255, v255, v78, v79
	v_mov_b32_e32 v210, v255
	s_nop 1
	v_permlane32_swap_b32_e32 v255, v210
	s_waitcnt lgkmcnt(0)
; __device__ __forceinline__ void partialSM(f32x16& p0, f32x16& p1, float& m_reg, float& mn, float& alpha) {
;     constexpr float C = SCALE * 1.4426950408889634f;
;     float pmax = p0[0];
; #pragma unroll
;     for (int r = 1; r < 16; ++r) pmax = fmaxf(pmax, p0[r]);
; #pragma unroll
;     for (int r = 0; r < 16; ++r) pmax = fmaxf(pmax, p1[r]);
;     { auto rr = __builtin_amdgcn_permlane32_swap(__float_as_uint(pmax), __float_as_uint(pmax), false, false);
;       pmax = fmaxf(__uint_as_float(rr[0]), __uint_as_float(rr[1])); }
;     if (__builtin_expect(__all(pmax - m_reg <= THR / SCALE), 1)) { mn = m_reg; alpha = 1.f; }
;     else { mn = fmaxf(m_reg, pmax); alpha = __builtin_amdgcn_exp2f((m_reg - mn) * C); m_reg = mn; }
;     const float mnC = -mn * C;
; #pragma unroll
;     for (int r = 0; r < 16; ++r) p0[r] = fmaf(p0[r], C, mnC);
; #pragma unroll
;     for (int r = 0; r < 16; ++r) p1[r] = fmaf(p1[r], C, mnC);
; #pragma unroll
;     for (int r = 0; r < 16; ++r) p0[r] = __builtin_amdgcn_exp2f(p0[r]);
; }
	v_mfma_f32_32x32x16_bf16 v[32:47], v[146:149], v[178:181], v[32:47]
	ds_read_b64_tr_b16 v[178:179], v159 offset:0x400
	ds_read_b64_tr_b16 v[180:181], v159 offset:0xc00
	v_max_f32_e32 v210, v210, v210
	v_max_f32_e32 v255, v255, v255
	v_max_f32_e32 v255, v255, v210
	v_sub_f32_e32 v210, v255, v134
	v_cmp_ge_f32_e32 vcc, s65, v210
	v_mfma_f32_32x32x16_bf16 v[32:47], v[166:169], v[182:185], v[32:47]
	ds_read_b64_tr_b16 v[182:183], v159 offset:0x1400
	ds_read_b64_tr_b16 v[184:185], v159 offset:0x1c00
	v_max_f32_e32 v210, v134, v134
	v_max_f32_e32 v210, v210, v255
	v_sub_f32_e32 v255, v134, v210
	v_mul_f32_e32 v255, 0x3e38aa3b, v255
	v_exp_f32_e32 v255, v255
	v_mfma_f32_32x32x16_bf16 v[32:47], v[170:173], v[186:189], v[32:47]
	ds_read_b64_tr_b16 v[186:187], v159 offset:0x2400
	ds_read_b64_tr_b16 v[188:189], v159 offset:0x2c00
	s_cmp_eq_u64 vcc, exec
	s_cselect_b64 s[8:9], -1, 0
	v_cndmask_b32_e64 v255, v255, 1.0, s[8:9]
	v_cndmask_b32_e64 v134, v210, v134, s[8:9]
	v_mul_f32_e32 v210, 0xbe38aa3b, v134
	v_mfma_f32_32x32x16_bf16 v[32:47], v[174:177], v[212:215], v[32:47]
	ds_read_b64_tr_b16 v[212:213], v159 offset:0x3400
	ds_read_b64_tr_b16 v[214:215], v159 offset:0x3c00
	v_pk_fma_f32 v[80:81], v[80:81], s[72:73], v[210:211] op_sel_hi:[1,0,0]
	v_pk_fma_f32 v[82:83], v[82:83], s[72:73], v[210:211] op_sel_hi:[1,0,0]
	v_pk_fma_f32 v[84:85], v[84:85], s[72:73], v[210:211] op_sel_hi:[1,0,0]
	v_pk_fma_f32 v[86:87], v[86:87], s[72:73], v[210:211] op_sel_hi:[1,0,0]
	v_pk_fma_f32 v[88:89], v[88:89], s[72:73], v[210:211] op_sel_hi:[1,0,0]
	s_waitcnt lgkmcnt(0)
	v_mfma_f32_32x32x16_bf16 v[16:31], v[146:149], v[178:181], v[16:31]
	ds_read_b64_tr_b16 v[178:179], v159 offset:0x600
	ds_read_b64_tr_b16 v[180:181], v159 offset:0xe00
	v_pk_fma_f32 v[90:91], v[90:91], s[72:73], v[210:211] op_sel_hi:[1,0,0]
	v_pk_fma_f32 v[92:93], v[92:93], s[72:73], v[210:211] op_sel_hi:[1,0,0]
	v_pk_fma_f32 v[94:95], v[94:95], s[72:73], v[210:211] op_sel_hi:[1,0,0]
	v_exp_f32_e32 v240, v80
	v_mfma_f32_32x32x16_bf16 v[16:31], v[166:169], v[182:185], v[16:31]
	ds_read_b64_tr_b16 v[182:183], v159 offset:0x1600
	ds_read_b64_tr_b16 v[184:185], v159 offset:0x1e00
	v_exp_f32_e32 v241, v81
	v_exp_f32_e32 v242, v82
	v_exp_f32_e32 v243, v83
	v_mfma_f32_32x32x16_bf16 v[16:31], v[170:173], v[186:189], v[16:31]
	ds_read_b64_tr_b16 v[186:187], v159 offset:0x2600
	ds_read_b64_tr_b16 v[188:189], v159 offset:0x2e00
	v_exp_f32_e32 v244, v84
	v_exp_f32_e32 v245, v85
	v_exp_f32_e32 v246, v86
	v_mfma_f32_32x32x16_bf16 v[16:31], v[174:177], v[212:215], v[16:31]
	ds_read_b64_tr_b16 v[212:213], v159 offset:0x3600
	ds_read_b64_tr_b16 v[214:215], v159 offset:0x3e00
	v_exp_f32_e32 v247, v87
	v_exp_f32_e32 v248, v88
	v_exp_f32_e32 v249, v89
	s_waitcnt lgkmcnt(0)
	v_mfma_f32_32x32x16_bf16 v[0:15], v[146:149], v[178:181], v[0:15]
	s_barrier
	s_waitcnt vmcnt(0)
	ds_write_b128 v163, v[114:117] offset:16384
	ds_write_b128 v164, v[126:129] offset:16384
	ds_write_b128 v161, v[118:121] offset:49152
	ds_write_b128 v162, v[122:125] offset:49152
	v_exp_f32_e32 v250, v90
	v_exp_f32_e32 v251, v91
	v_exp_f32_e32 v206, v92
	v_mfma_f32_32x32x16_bf16 v[0:15], v[166:169], v[182:185], v[0:15]
	v_exp_f32_e32 v207, v93
	v_exp_f32_e32 v208, v94
	v_exp_f32_e32 v209, v95
	v_mfma_f32_32x32x16_bf16 v[0:15], v[170:173], v[186:189], v[0:15]
	v_mfma_f32_32x32x16_bf16 v[0:15], v[174:177], v[212:215], v[0:15]
	v_mov_b32_e32 v137, v255
	s_cmp_lg_u64 s[8:9], 0
	s_cbranch_scc1 .LBB0_288
	s_and_saveexec_b64 s[2:3], s[6:7]
	ds_write_b32 v157, v137 offset:128
	s_or_b64 exec, exec, s[2:3]
	s_waitcnt lgkmcnt(0)
	ds_read_b128 v[114:117], v158 offset:224
	ds_read_b128 v[118:121], v158 offset:192
	ds_read_b128 v[122:125], v158 offset:160
	ds_read_b128 v[126:129], v158 offset:128
	s_waitcnt lgkmcnt(3)
	v_pk_mul_f32 v[62:63], v[62:63], v[116:117]
	s_waitcnt lgkmcnt(2)
	v_pk_mul_f32 v[58:59], v[58:59], v[120:121]
	s_waitcnt lgkmcnt(1)
	v_pk_mul_f32 v[54:55], v[54:55], v[124:125]
	s_waitcnt lgkmcnt(0)
	v_pk_mul_f32 v[50:51], v[50:51], v[128:129]
	v_pk_mul_f32 v[60:61], v[60:61], v[114:115]
	v_pk_mul_f32 v[56:57], v[56:57], v[118:119]
	v_pk_mul_f32 v[52:53], v[52:53], v[122:123]
	v_pk_mul_f32 v[48:49], v[48:49], v[126:127]
	v_pk_mul_f32 v[46:47], v[46:47], v[116:117]
	v_pk_mul_f32 v[42:43], v[42:43], v[120:121]
	v_pk_mul_f32 v[38:39], v[38:39], v[124:125]
	v_pk_mul_f32 v[34:35], v[34:35], v[128:129]
	v_pk_mul_f32 v[44:45], v[44:45], v[114:115]
	v_pk_mul_f32 v[40:41], v[40:41], v[118:119]
	v_pk_mul_f32 v[36:37], v[36:37], v[122:123]
	v_pk_mul_f32 v[32:33], v[32:33], v[126:127]
	v_pk_mul_f32 v[30:31], v[30:31], v[116:117]
	v_pk_mul_f32 v[26:27], v[26:27], v[120:121]
	v_pk_mul_f32 v[22:23], v[22:23], v[124:125]
	v_pk_mul_f32 v[18:19], v[18:19], v[128:129]
	v_pk_mul_f32 v[28:29], v[28:29], v[114:115]
	v_pk_mul_f32 v[24:25], v[24:25], v[118:119]
	v_pk_mul_f32 v[20:21], v[20:21], v[122:123]
	v_pk_mul_f32 v[16:17], v[16:17], v[126:127]
	v_pk_mul_f32 v[14:15], v[14:15], v[116:117]
	v_pk_mul_f32 v[10:11], v[10:11], v[120:121]
	v_pk_mul_f32 v[6:7], v[6:7], v[124:125]
	v_pk_mul_f32 v[2:3], v[2:3], v[128:129]
	v_pk_mul_f32 v[12:13], v[12:13], v[114:115]
	v_pk_mul_f32 v[8:9], v[8:9], v[118:119]
	v_pk_mul_f32 v[4:5], v[4:5], v[122:123]
	v_pk_mul_f32 v[0:1], v[0:1], v[126:127]
